# P5: vT fragments of k-steps 4 and 5 requested at the item start (in flight during q~ staging and step A) instead of after k-steps 0/1
# speedup vs baseline: 1.0045x; 1.0045x over previous
.Lp5c_skip:
	global_load_dwordx4 v[50:53], v[8:9], off offset:192
	s_lshl_b32 s99, s74, 14
	s_lshl_b32 s100, s73, 9
	s_add_u32 s99, s99, s100
	s_add_u32 s100, s99, s31
	s_addc_u32 s101, s46, 0
	v_or_b32_e32 v86, s100, v169
	v_mov_b32_e32 v87, s101
	s_mov_b32 s100, 0x20000
	s_mov_b32 s101, 0
	v_lshlrev_b64 v[86:87], 6, v[86:87]
	v_lshl_add_u64 v[86:87], s[20:21], 0, v[86:87]
	v_lshl_add_u64 v[86:87], v[86:87], 0, v[162:163]
	v_lshl_add_u64 v[88:89], v[86:87], 0, s[100:101]
	global_load_dwordx4 v[134:137], v[86:87], off
	global_load_dwordx4 v[130:133], v[86:87], off offset:1024
	global_load_dwordx4 v[126:129], v[86:87], off offset:2048
	global_load_dwordx4 v[54:57], v[86:87], off offset:3072
	global_load_dwordx4 v[70:73], v[88:89], off
	global_load_dwordx4 v[74:77], v[88:89], off offset:1024
	global_load_dwordx4 v[78:81], v[88:89], off offset:2048
	global_load_dwordx4 v[82:85], v[88:89], off offset:3072
	v_add_u32_e32 v2, s72, v108
	v_mad_i64_i32 v[2:3], s[6:7], v2, s66, v[164:165]
	s_lshl_b32 s26, s73, 8
	v_lshlrev_b32_e32 v4, 4, v170
	v_lshl_add_u64 v[2:3], v[2:3], 0, s[26:27]
	v_and_b32_e32 v4, 0xf0, v4
	v_mov_b32_e32 v5, v163
	v_lshl_add_u64 v[2:3], v[2:3], 0, v[4:5]
	v_lshl_add_u64 v[106:107], v[2:3], 0, s[28:29]
	s_and_b64 vcc, exec, s[4:5]
	v_mov_b32_e32 v2, 0
	v_mov_b32_e32 v3, 0
	v_mov_b32_e32 v4, 0
	v_mov_b32_e32 v5, 0
	s_cbranch_vccnz .LBB0_430
	global_load_dwordx4 v[2:5], v[106:107], off

.LBB0_444:
	v_xor_b32_e32 v106, v108, v170
	v_lshlrev_b32_e32 v106, 4, v106
	v_lshlrev_b32_e32 v107, 8, v108
	v_and_or_b32 v106, v106, s67, v107
	v_add_u32_e32 v107, 0, v106
	s_and_b64 vcc, exec, s[4:5]
	s_cmp_eq_u32 s98, 0
	s_cbranch_scc1 .Lp5c_w2
	s_waitcnt vmcnt(25)
	ds_write_b128 v107, v[22:25]
	s_waitcnt vmcnt(24)
	ds_write_b128 v107, v[18:21] offset:8192
	s_branch .Lp5c_wj
.Lp5c_w2:
	s_waitcnt vmcnt(10)
	ds_write_b128 v107, v[22:25]
	s_waitcnt vmcnt(9)
	ds_write_b128 v107, v[18:21] offset:8192

.LBB0_456:
	v_bfe_u32 v138, v170, 4, 2
	v_lshl_add_u32 v139, v169, 8, 0
	v_xor_b32_e32 v2, v138, v169
	s_lshl_b32 s6, s74, 3
	v_lshl_add_u32 v98, v2, 4, v139
	s_ashr_i32 s7, s6, 31
	s_waitcnt lgkmcnt(0)
	s_barrier
	ds_read_b128 v[2:5], v98
	ds_read_b128 v[10:13], v98 offset:4096
	ds_read_b128 v[90:93], v98 offset:8192
	ds_read_b128 v[98:101], v98 offset:12288
	s_lshl_b64 s[6:7], s[6:7], 11
	s_lshl_b32 s73, s73, 9
	s_add_u32 s8, s73, s31
	s_addc_u32 s9, 0, s46
	s_add_u32 s6, s8, s6
	s_addc_u32 s7, s9, s7
	s_waitcnt lgkmcnt(3)
	s_waitcnt vmcnt(0)
	v_mfma_f32_16x16x32_bf16 v[6:9], v[192:195], v[2:5], 0
	v_mov_b32_e32 v123, s7
	v_or_b32_e32 v122, s6, v169
	v_lshlrev_b32_e32 v124, 3, v138
	s_waitcnt lgkmcnt(2)
	v_mfma_f32_16x16x32_bf16 v[14:17], v[192:195], v[10:13], 0
	v_lshlrev_b64 v[122:123], 6, v[122:123]
	v_lshl_add_u64 v[122:123], s[20:21], 0, v[122:123]
	v_lshlrev_b32_e32 v124, 1, v124
	s_waitcnt lgkmcnt(1)
	v_mfma_f32_16x16x32_bf16 v[94:97], v[192:195], v[90:93], 0
	v_mov_b32_e32 v125, v163
	v_lshl_add_u64 v[166:167], v[122:123], 0, v[124:125]
	s_waitcnt lgkmcnt(0)
	v_mfma_f32_16x16x32_bf16 v[66:69], v[192:195], v[98:101], 0
	v_mfma_f32_16x16x32_bf16 v[102:105], v[248:251], v[2:5], 0
	v_mfma_f32_16x16x32_bf16 v[106:109], v[248:251], v[10:13], 0
	v_mfma_f32_16x16x32_bf16 v[110:113], v[248:251], v[90:93], 0
	v_mfma_f32_16x16x32_bf16 v[86:89], v[248:251], v[98:101], 0
	v_mfma_f32_16x16x32_bf16 v[114:117], v[200:203], v[2:5], 0
	v_mfma_f32_16x16x32_bf16 v[118:121], v[200:203], v[10:13], 0
	v_mfma_f32_16x16x32_bf16 v[140:143], v[200:203], v[90:93], 0
	v_mfma_f32_16x16x32_bf16 v[46:49], v[200:203], v[98:101], 0
	v_mfma_f32_16x16x32_bf16 v[2:5], v[232:235], v[2:5], 0
	v_mfma_f32_16x16x32_bf16 v[10:13], v[232:235], v[10:13], 0
	v_mfma_f32_16x16x32_bf16 v[90:93], v[232:235], v[90:93], 0
	v_mfma_f32_16x16x32_bf16 v[42:45], v[232:235], v[98:101], 0
	v_mov_b32_e32 v122, v54
	v_mov_b32_e32 v123, v55
	v_mov_b32_e32 v124, v56
	v_mov_b32_e32 v125, v57
	v_bitop3_b32 v98, v138, v169, 4 bitop3:0x36
	v_lshl_add_u32 v152, v98, 4, v139
	ds_read_b128 v[98:101], v152
	ds_read_b128 v[144:147], v152 offset:4096
	ds_read_b128 v[148:151], v152 offset:8192
	ds_read_b128 v[152:155], v152 offset:12288
	s_waitcnt lgkmcnt(3)
	v_mfma_f32_16x16x32_bf16 v[6:9], v[196:199], v[98:101], v[6:9]
	s_waitcnt lgkmcnt(2)
	v_mfma_f32_16x16x32_bf16 v[14:17], v[196:199], v[144:147], v[14:17]
	s_waitcnt lgkmcnt(1)
	v_mfma_f32_16x16x32_bf16 v[94:97], v[196:199], v[148:151], v[94:97]
	s_waitcnt lgkmcnt(0)
	v_mfma_f32_16x16x32_bf16 v[34:37], v[196:199], v[152:155], v[66:69]
	v_mfma_f32_16x16x32_bf16 v[66:69], v[208:211], v[98:101], v[102:105]
	v_mfma_f32_16x16x32_bf16 v[102:105], v[208:211], v[144:147], v[106:109]
	v_mfma_f32_16x16x32_bf16 v[156:159], v[208:211], v[148:151], v[110:113]
	v_mfma_f32_16x16x32_bf16 v[38:41], v[208:211], v[152:155], v[86:89]
	v_mfma_f32_16x16x32_bf16 v[86:89], v[204:207], v[98:101], v[114:117]
	v_mfma_f32_16x16x32_bf16 v[98:101], v[216:219], v[98:101], v[2:5]
	v_mfma_f32_16x16x32_bf16 v[172:175], v[204:207], v[144:147], v[118:121]
	v_mfma_f32_16x16x32_bf16 v[140:143], v[204:207], v[148:151], v[140:143]
	v_mfma_f32_16x16x32_bf16 v[176:179], v[204:207], v[152:155], v[46:49]
	v_mfma_f32_16x16x32_bf16 v[144:147], v[216:219], v[144:147], v[10:13]
	v_mfma_f32_16x16x32_bf16 v[148:151], v[216:219], v[148:151], v[90:93]
	v_mfma_f32_16x16x32_bf16 v[152:155], v[216:219], v[152:155], v[42:45]
	v_add_co_u32_e32 v2, vcc, s69, v166
	s_nop 1
	v_addc_co_u32_e32 v3, vcc, 0, v167, vcc
	v_mov_b32_e32 v118, v70
	v_mov_b32_e32 v119, v71
	v_mov_b32_e32 v120, v72
	v_mov_b32_e32 v121, v73
	v_mov_b32_e32 v114, v74
	v_mov_b32_e32 v115, v75
	v_mov_b32_e32 v116, v76
	v_mov_b32_e32 v117, v77
	v_mov_b32_e32 v110, v78
	v_mov_b32_e32 v111, v79
	v_mov_b32_e32 v112, v80
	v_mov_b32_e32 v113, v81
	v_mov_b32_e32 v106, v82
	v_mov_b32_e32 v107, v83
	v_mov_b32_e32 v108, v84
	v_mov_b32_e32 v109, v85
	v_bitop3_b32 v2, v138, v169, 8 bitop3:0x36
	v_lshl_add_u32 v26, v2, 4, v139
	ds_read_b128 v[90:93], v26
	ds_read_b128 v[180:183], v26 offset:4096
	ds_read_b128 v[184:187], v26 offset:8192
	ds_read_b128 v[188:191], v26 offset:12288
	s_waitcnt lgkmcnt(3)
	v_mfma_f32_16x16x32_bf16 v[2:5], v[224:227], v[90:93], v[6:9]
	s_waitcnt lgkmcnt(2)
	v_mfma_f32_16x16x32_bf16 v[6:9], v[224:227], v[180:183], v[14:17]
	s_waitcnt lgkmcnt(1)
	v_mfma_f32_16x16x32_bf16 v[10:13], v[224:227], v[184:187], v[94:97]
	s_waitcnt lgkmcnt(0)
	v_mfma_f32_16x16x32_bf16 v[14:17], v[224:227], v[188:191], v[34:37]
	v_mfma_f32_16x16x32_bf16 v[26:29], v[212:215], v[90:93], v[66:69]
	v_mfma_f32_16x16x32_bf16 v[30:33], v[212:215], v[180:183], v[102:105]
	v_mfma_f32_16x16x32_bf16 v[34:37], v[212:215], v[184:187], v[156:159]
	v_mfma_f32_16x16x32_bf16 v[38:41], v[212:215], v[188:191], v[38:41]
	v_mfma_f32_16x16x32_bf16 v[42:45], v[240:243], v[90:93], v[86:89]
	v_mfma_f32_16x16x32_bf16 v[46:49], v[240:243], v[180:183], v[172:175]
	v_mfma_f32_16x16x32_bf16 v[66:69], v[240:243], v[184:187], v[140:143]
	v_mfma_f32_16x16x32_bf16 v[86:89], v[240:243], v[188:191], v[176:179]
	v_mfma_f32_16x16x32_bf16 v[90:93], v[220:223], v[90:93], v[98:101]
	v_mfma_f32_16x16x32_bf16 v[94:97], v[220:223], v[180:183], v[144:147]
	v_mfma_f32_16x16x32_bf16 v[98:101], v[220:223], v[184:187], v[148:151]
	v_mfma_f32_16x16x32_bf16 v[102:105], v[220:223], v[188:191], v[152:155]
	s_cmp_lg_u32 s75, 0
	s_cselect_b64 s[6:7], -1, 0
	s_cmp_eq_u32 s75, 0
	s_cbranch_scc1 .LBB0_458
	v_add_co_u32_e32 v70, vcc, 0x40000, v166
	s_nop 1
	v_addc_co_u32_e32 v71, vcc, 0, v167, vcc
	global_load_dwordx4 v[82:85], v[70:71], off
	global_load_dwordx4 v[74:77], v[70:71], off offset:1024
	global_load_dwordx4 v[78:81], v[70:71], off offset:2048
	s_nop 0
	global_load_dwordx4 v[70:73], v[70:71], off offset:3072
